# v89 stack + the P1-exit vmcnt(0) store drain skipped on the CUs that go straight into the P11 GEMM (the post-P11 grid sync still drains)
# baseline (speedup 1.0000x reference)
; #define PG8_WAIT_V(n) asm volatile("s_waitcnt vmcnt(" #n ")" ::: "memory")
; #define PG8_BAR __builtin_amdgcn_s_barrier()
; #define PH(n) if (ONLY < 0 || ONLY == (n))
; #define WSB(off) ((bf16*)((unsigned char*)KARG(20) + (off)))
; template <class Epi, class Sched>
; __device__ __forceinline__ void gemm_phase(PG8_LAS unsigned char* lds, PG8_LAS unsigned char* xl, const Gemm g, const Sched& S, const Epi& E) {
;     ...
;     PG8_WAIT_V(0);
;     PG8_BAR;
; __global__ void __launch_bounds__(NWAVES * 64, 2) mk_fwd(Args args) {
;     ...
;     PH(11) { PHASE_VARS
;         pg8::Gemm g{WSB(WS_MEMN), WSB(WS_WMKV), DM, DM, DM}; pg8::Sched2D S; S.init(NB * ML, 2 * DM, G, bx, DM, DM);
;         pg8::EpiBf16 E{WSB(WS_KVM), 2 * DM, 0, 0, 1.f};
;         pg8::gemm_phase(lds, xl, g, S, E);
.LBB0_112:
	s_cmpk_lt_i32 s39, 0x80
	s_cbranch_scc1 .Lp1_nodrain
	s_waitcnt vmcnt(0)
.Lp1_nodrain:
	s_barrier
.LBB0_113:
	v_mov_b32_e32 v0, v220
	s_mov_b32 s33, s39
	v_mov_b32_e32 v8, v220
	s_load_dwordx2 s[2:3], s[0:1], 0xa0
	s_load_dwordx2 s[6:7], s[0:1], 0xa0
	s_load_dwordx2 s[4:5], s[0:1], 0xa0
	s_waitcnt lgkmcnt(0)
	s_cmpk_lt_i32 s33, 0x80
	v_readfirstlane_b32 s12, v8
	s_cbranch_scc0 .LBB0_137
	s_ashr_i32 s34, s33, 31
	s_lshr_b32 s8, s34, 29
	s_add_i32 s13, s33, s8
	s_and_b32 s8, s13, -8
	s_sub_i32 s11, s33, s8
	s_cmp_gt_i32 s11, -1
	s_cbranch_scc0 .LBB0_116
	s_lshl_b32 s10, s11, 4
	s_ashr_i32 s8, s13, 3
	s_cbranch_execz .LBB0_117
	s_branch .LBB0_118
